# v126 + residual GEMM epilogue: all 32 x loads consumed first (results stay in the accumulators), then the 32 stores in one burst (load waits no longer cover store acks)
# speedup vs baseline: 1.0111x; 1.0050x over previous
.LBB0_519:
	s_min_i32 s25, s47, 0x80
	s_lshr_b32 s25, s25, 4
	s_mul_i32 s40, s25, 0x1800
	s_ashr_i32 s41, s40, 31
	s_lshl_b64 s[40:41], s[40:41], 2
	s_add_u32 s42, s18, s40
	s_addc_u32 s43, s19, s41
	s_cmpk_lt_i32 s47, 0x80
	v_lshl_add_u32 v146, s47, 18, v143
	v_add_u32_e32 v0, 0xfe000000, v146
	s_cselect_b64 vcc, -1, 0
	v_lshl_or_b32 v140, s46, 8, v144
	v_cndmask_b32_e32 v147, v0, v146, vcc
	s_and_b64 s[40:41], vcc, exec
	v_add_u32_e32 v0, v147, v140
	s_cselect_b32 s41, s15, s55
	s_cselect_b32 s40, s16, s54
	v_lshlrev_b64 v[152:153], 2, v[0:1]
	v_mov_b32_e32 v141, v1
	v_lshl_add_u64 v[146:147], s[40:41], 0, v[152:153]
	v_lshl_add_u64 v[138:139], v[140:141], 2, s[42:43]
	global_load_dwordx4 v[172:175], v[138:139], off
	global_load_dwordx4 v[176:179], v[138:139], off offset:64
	global_load_dwordx4 v[180:183], v[138:139], off offset:512
	global_load_dwordx4 v[184:187], v[138:139], off offset:576
	v_readlane_b32 s56, v254, 4
	v_readlane_b32 s70, v254, 18
	v_readlane_b32 s71, v254, 19
	s_cselect_b32 s43, s71, s55
	s_cselect_b32 s42, s70, s54
	v_lshl_add_u64 v[152:153], s[42:43], 0, v[152:153]
	v_readlane_b32 s57, v254, 5
	v_readlane_b32 s58, v254, 6
	v_readlane_b32 s59, v254, 7
	v_readlane_b32 s60, v254, 8
	v_readlane_b32 s61, v254, 9
	v_readlane_b32 s62, v254, 10
	v_readlane_b32 s63, v254, 11
	v_readlane_b32 s64, v254, 12
	v_readlane_b32 s65, v254, 13
	v_readlane_b32 s66, v254, 14
	v_readlane_b32 s67, v254, 15
	v_readlane_b32 s68, v254, 16
	v_readlane_b32 s69, v254, 17
	s_mov_b64 s[40:41], 0x10000
	s_mov_b64 s[42:43], 0x50000
	global_load_dwordx4 v[148:151], v[146:147], off
	global_load_dwordx4 v[168:171], v[146:147], off offset:64
	global_load_dwordx4 v[188:191], v[146:147], off offset:512
	global_load_dwordx4 v[192:195], v[146:147], off offset:576
	v_lshl_add_u64 v[146:147], v[146:147], 0, s[40:41]
	global_load_dwordx4 v[196:199], v[146:147], off
	global_load_dwordx4 v[200:203], v[146:147], off offset:64
	global_load_dwordx4 v[204:207], v[146:147], off offset:512
	global_load_dwordx4 v[208:211], v[146:147], off offset:576
	v_lshl_add_u64 v[146:147], v[146:147], 0, s[40:41]
	global_load_dwordx4 v[212:215], v[146:147], off
	global_load_dwordx4 v[224:227], v[146:147], off offset:64
	global_load_dwordx4 v[234:237], v[146:147], off offset:512
	global_load_dwordx4 v[238:241], v[146:147], off offset:576
	s_waitcnt vmcnt(11)
	v_pk_fma_f32 v[128:129], v[128:129], v[174:175], v[150:151]
	v_pk_fma_f32 v[126:127], v[126:127], v[172:173], v[148:149]
	v_lshl_add_u64 v[146:147], v[146:147], 0, s[40:41]
	global_load_dwordx4 v[148:151], v[146:147], off
	s_waitcnt vmcnt(11)
	v_pk_fma_f32 v[124:125], v[124:125], v[178:179], v[170:171]
	v_pk_fma_f32 v[122:123], v[122:123], v[176:177], v[168:169]
	global_load_dwordx4 v[168:171], v[146:147], off offset:64
	s_waitcnt vmcnt(11)
	v_pk_fma_f32 v[120:121], v[120:121], v[182:183], v[190:191]
	v_pk_fma_f32 v[118:119], v[118:119], v[180:181], v[188:189]
	global_load_dwordx4 v[188:191], v[146:147], off offset:512
	s_waitcnt vmcnt(11)
	v_pk_fma_f32 v[112:113], v[112:113], v[186:187], v[194:195]
	v_pk_fma_f32 v[110:111], v[110:111], v[184:185], v[192:193]
	global_load_dwordx4 v[192:195], v[146:147], off offset:576
	s_waitcnt vmcnt(11)
	v_pk_fma_f32 v[116:117], v[116:117], v[174:175], v[198:199]
	v_pk_fma_f32 v[114:115], v[114:115], v[172:173], v[196:197]
	v_lshl_add_u64 v[146:147], v[146:147], 0, s[42:43]
	global_load_dwordx4 v[196:199], v[146:147], off
	s_waitcnt vmcnt(11)
	v_pk_fma_f32 v[108:109], v[108:109], v[178:179], v[202:203]
	v_pk_fma_f32 v[106:107], v[106:107], v[176:177], v[200:201]
	global_load_dwordx4 v[200:203], v[146:147], off offset:64
	s_waitcnt vmcnt(11)
	v_pk_fma_f32 v[104:105], v[104:105], v[182:183], v[206:207]
	v_pk_fma_f32 v[102:103], v[102:103], v[180:181], v[204:205]
	global_load_dwordx4 v[204:207], v[146:147], off offset:512
	s_waitcnt vmcnt(11)
	v_pk_fma_f32 v[96:97], v[96:97], v[186:187], v[210:211]
	v_pk_fma_f32 v[94:95], v[94:95], v[184:185], v[208:209]
	global_load_dwordx4 v[208:211], v[146:147], off offset:576
	s_waitcnt vmcnt(11)
	v_pk_fma_f32 v[100:101], v[100:101], v[174:175], v[214:215]
	v_pk_fma_f32 v[98:99], v[98:99], v[172:173], v[212:213]
	v_lshl_add_u64 v[146:147], v[146:147], 0, s[40:41]
	global_load_dwordx4 v[212:215], v[146:147], off
	s_waitcnt vmcnt(11)
	v_pk_fma_f32 v[92:93], v[92:93], v[178:179], v[226:227]
	v_pk_fma_f32 v[90:91], v[90:91], v[176:177], v[224:225]
	global_load_dwordx4 v[224:227], v[146:147], off offset:64
	s_waitcnt vmcnt(11)
	v_pk_fma_f32 v[88:89], v[88:89], v[182:183], v[236:237]
	v_pk_fma_f32 v[86:87], v[86:87], v[180:181], v[234:235]
	global_load_dwordx4 v[234:237], v[146:147], off offset:512
	s_waitcnt vmcnt(11)
	v_pk_fma_f32 v[80:81], v[80:81], v[186:187], v[240:241]
	v_pk_fma_f32 v[78:79], v[78:79], v[184:185], v[238:239]
	global_load_dwordx4 v[238:241], v[146:147], off offset:576
	s_waitcnt vmcnt(11)
	v_pk_fma_f32 v[84:85], v[84:85], v[174:175], v[150:151]
	v_pk_fma_f32 v[82:83], v[82:83], v[172:173], v[148:149]
	v_lshl_add_u64 v[146:147], v[146:147], 0, s[40:41]
	global_load_dwordx4 v[148:151], v[146:147], off
	s_waitcnt vmcnt(11)
	v_pk_fma_f32 v[76:77], v[76:77], v[178:179], v[170:171]
	v_pk_fma_f32 v[74:75], v[74:75], v[176:177], v[168:169]
	global_load_dwordx4 v[168:171], v[146:147], off offset:64
	s_waitcnt vmcnt(11)
	v_pk_fma_f32 v[72:73], v[72:73], v[182:183], v[190:191]
	v_pk_fma_f32 v[70:71], v[70:71], v[180:181], v[188:189]
	global_load_dwordx4 v[188:191], v[146:147], off offset:512
	s_waitcnt vmcnt(11)
	v_pk_fma_f32 v[68:69], v[68:69], v[186:187], v[194:195]
	v_pk_fma_f32 v[66:67], v[66:67], v[184:185], v[192:193]
	global_load_dwordx4 v[192:195], v[146:147], off offset:576
	s_waitcnt vmcnt(11)
	v_pk_fma_f32 v[64:65], v[64:65], v[174:175], v[198:199]
	v_pk_fma_f32 v[62:63], v[62:63], v[172:173], v[196:197]
	v_lshl_add_u64 v[146:147], v[146:147], 0, s[40:41]
	global_load_dwordx4 v[196:199], v[146:147], off
	s_waitcnt vmcnt(11)
	v_pk_fma_f32 v[60:61], v[60:61], v[178:179], v[202:203]
	v_pk_fma_f32 v[58:59], v[58:59], v[176:177], v[200:201]
	global_load_dwordx4 v[200:203], v[146:147], off offset:64
	s_waitcnt vmcnt(11)
	v_pk_fma_f32 v[56:57], v[56:57], v[182:183], v[206:207]
	v_pk_fma_f32 v[54:55], v[54:55], v[180:181], v[204:205]
	global_load_dwordx4 v[204:207], v[146:147], off offset:512
	s_waitcnt vmcnt(11)
	v_pk_fma_f32 v[48:49], v[48:49], v[186:187], v[210:211]
	v_pk_fma_f32 v[46:47], v[46:47], v[184:185], v[208:209]
	global_load_dwordx4 v[208:211], v[146:147], off offset:576
	s_waitcnt vmcnt(11)
	v_pk_fma_f32 v[52:53], v[52:53], v[174:175], v[214:215]
	v_pk_fma_f32 v[50:51], v[50:51], v[172:173], v[212:213]
	s_waitcnt vmcnt(10)
	v_pk_fma_f32 v[44:45], v[44:45], v[178:179], v[226:227]
	v_pk_fma_f32 v[42:43], v[42:43], v[176:177], v[224:225]
	s_waitcnt vmcnt(9)
	v_pk_fma_f32 v[40:41], v[40:41], v[182:183], v[236:237]
	v_pk_fma_f32 v[38:39], v[38:39], v[180:181], v[234:235]
	s_waitcnt vmcnt(8)
	v_pk_fma_f32 v[32:33], v[32:33], v[186:187], v[240:241]
	v_pk_fma_f32 v[30:31], v[30:31], v[184:185], v[238:239]
	s_waitcnt vmcnt(7)
	v_pk_fma_f32 v[36:37], v[36:37], v[174:175], v[150:151]
	v_pk_fma_f32 v[34:35], v[34:35], v[172:173], v[148:149]
	s_waitcnt vmcnt(6)
	v_pk_fma_f32 v[28:29], v[28:29], v[178:179], v[170:171]
	v_pk_fma_f32 v[26:27], v[26:27], v[176:177], v[168:169]
	s_waitcnt vmcnt(5)
	v_pk_fma_f32 v[24:25], v[24:25], v[182:183], v[190:191]
	v_pk_fma_f32 v[22:23], v[22:23], v[180:181], v[188:189]
	s_waitcnt vmcnt(4)
	v_pk_fma_f32 v[16:17], v[16:17], v[186:187], v[194:195]
	v_pk_fma_f32 v[14:15], v[14:15], v[184:185], v[192:193]
	s_waitcnt vmcnt(3)
	v_pk_fma_f32 v[20:21], v[20:21], v[174:175], v[198:199]
	v_pk_fma_f32 v[18:19], v[18:19], v[172:173], v[196:197]
	s_waitcnt vmcnt(2)
	v_pk_fma_f32 v[12:13], v[12:13], v[178:179], v[202:203]
	v_pk_fma_f32 v[10:11], v[10:11], v[176:177], v[200:201]
	s_waitcnt vmcnt(1)
	v_pk_fma_f32 v[8:9], v[8:9], v[182:183], v[206:207]
	v_pk_fma_f32 v[6:7], v[6:7], v[180:181], v[204:205]
	s_waitcnt vmcnt(0)
	v_pk_fma_f32 v[4:5], v[4:5], v[186:187], v[210:211]
	v_pk_fma_f32 v[2:3], v[2:3], v[184:185], v[208:209]
	global_store_dwordx4 v[152:153], v[126:129], off
	global_store_dwordx4 v[152:153], v[122:125], off offset:64
	global_store_dwordx4 v[152:153], v[118:121], off offset:512
	global_store_dwordx4 v[152:153], v[110:113], off offset:576
	v_lshl_add_u64 v[152:153], v[152:153], 0, s[40:41]
	global_store_dwordx4 v[152:153], v[114:117], off
	global_store_dwordx4 v[152:153], v[106:109], off offset:64
	global_store_dwordx4 v[152:153], v[102:105], off offset:512
	global_store_dwordx4 v[152:153], v[94:97], off offset:576
	v_lshl_add_u64 v[152:153], v[152:153], 0, s[40:41]
	global_store_dwordx4 v[152:153], v[98:101], off
	global_store_dwordx4 v[152:153], v[90:93], off offset:64
	global_store_dwordx4 v[152:153], v[86:89], off offset:512
	global_store_dwordx4 v[152:153], v[78:81], off offset:576
	v_lshl_add_u64 v[152:153], v[152:153], 0, s[40:41]
	global_store_dwordx4 v[152:153], v[82:85], off
	global_store_dwordx4 v[152:153], v[74:77], off offset:64
	global_store_dwordx4 v[152:153], v[70:73], off offset:512
	global_store_dwordx4 v[152:153], v[66:69], off offset:576
	v_lshl_add_u64 v[152:153], v[152:153], 0, s[42:43]
	global_store_dwordx4 v[152:153], v[62:65], off
	global_store_dwordx4 v[152:153], v[58:61], off offset:64
	global_store_dwordx4 v[152:153], v[54:57], off offset:512
	global_store_dwordx4 v[152:153], v[46:49], off offset:576
	v_lshl_add_u64 v[152:153], v[152:153], 0, s[40:41]
	global_store_dwordx4 v[152:153], v[50:53], off
	global_store_dwordx4 v[152:153], v[42:45], off offset:64
	global_store_dwordx4 v[152:153], v[38:41], off offset:512
	global_store_dwordx4 v[152:153], v[30:33], off offset:576
	v_lshl_add_u64 v[152:153], v[152:153], 0, s[40:41]
	global_store_dwordx4 v[152:153], v[34:37], off
	global_store_dwordx4 v[152:153], v[26:29], off offset:64
	global_store_dwordx4 v[152:153], v[22:25], off offset:512
	global_store_dwordx4 v[152:153], v[14:17], off offset:576
	v_lshl_add_u64 v[152:153], v[152:153], 0, s[40:41]
	global_store_dwordx4 v[152:153], v[18:21], off
	global_store_dwordx4 v[152:153], v[10:13], off offset:64
	global_store_dwordx4 v[152:153], v[6:9], off offset:512
	global_store_dwordx4 v[152:153], v[2:5], off offset:576
	s_andn2_b64 vcc, exec, s[38:39]
	s_mov_b64 s[38:39], -1
	s_cbranch_vccnz .LBB0_508
	s_andn2_b64 vcc, exec, s[2:3]
	s_cbranch_vccnz .LBB0_507
	s_barrier
	s_branch .LBB0_507
